# FoX: forget-bias accumulator init (cqm - ck) done with v_pk_add_f32 pairs instead of scalar v_sub_f32 (48 fewer VALU per tile iteration)
# speedup vs baseline: 1.0026x; 1.0004x over previous
; #define LAS __attribute__((address_space(3)))
; #define FX_LOAD(T) do { const bf16_t* rp = proj + (rowbase + 128 * (T) + krow) * NPROJ + h * 64 + chunk * 8; \
;         kreg[0] = *(const u32x4*)(rp + C_FK); kreg[1] = *(const u32x4*)(rp + C_FK + 32); vreg[0] = *(const u32x4*)(rp + C_FV); vreg[1] = *(const u32x4*)(rp + C_FV + 32); \
;         if (tid < 128) ckreg = FX_C2(128 * (T) + tid); } while (0)
; DI void fx_init(f32x16& p0, f32x16& p1, const LAS float* ck, float cqm, int hi) {
; #pragma unroll
;     for (int g = 0; g < 4; ++g) { const f32x4 c0 = *(const LAS f32x4*)(ck + 8 * g + 4 * hi), c1 = *(const LAS f32x4*)(ck + 32 + 8 * g + 4 * hi);
; #pragma unroll
;         for (int e = 0; e < 4; ++e) { p0[4 * g + e] = cqm - c0[e]; p1[4 * g + e] = cqm - c1[e]; } }
; }
; DI void fx_qk(f32x16& p0, f32x16& p1, const LAS bf16_t* Kt, const bf16x8 (&qr)[4], int r32, int hi) {
; #pragma unroll
;     for (int ks = 0; ks < 4; ++ks) { const bf16x8 a0 = *(const LAS bf16x8*)(Kt + r32 * 72 + 16 * ks + 8 * hi), a1 = *(const LAS bf16x8*)(Kt + (32 + r32) * 72 + 16 * ks + 8 * hi);
;         p0 = __builtin_amdgcn_mfma_f32_32x32x16_bf16(a0, qr[ks], p0, 0, 0, 0); p1 = __builtin_amdgcn_mfma_f32_32x32x16_bf16(a1, qr[ks], p1, 0, 0, 0); }
; DI void fox_unit(int bh, int qb, const Params& p, LAS unsigned char* lds, float thr2) {
;     ...
;     for (int T = T_hi; T >= T_lo; --T) {
;         const int buf = (T_hi - T) & 1;
;         if (T > T_lo) FX_LOAD(T - 1);
;         { const int k1 = 128 * T + 64, k0s = 128 * T;
;           const LAS float* ckT = ckb + buf * 128; const LAS bf16_t* KtT = Kb + buf * 9216; const LAS bf16_t* VtT = Vb + buf * 9216;
;           const bool act1 = (k1 <= qw0 + 31) && (2 * T + 1 >= t_lo), act0 = (k0s <= qw0 + 31) && (2 * T >= t_lo);
;           if (act1 && act0) {
;               f32x16 a0, a1, b0, b1; bf16x8 vfr[4][2], pw[4];
;               fx_init(a0, a1, ckT + 64, cqm, hi); fx_init(b0, b1, ckT, cqm, hi);
;               fx_qk(a0, a1, KtT + 64 * FX_KP, qr, r32, hi);
;               fx_qk(b0, b1, KtT, qr, r32, hi);
;               fx_vfrag(vfr, VtT + 64 * FX_KP, lane, hi);
;               __builtin_amdgcn_sched_barrier(0);
;               fx_softmax<true>(a0, a1, b0, b1, pw, o, m, l, cqm, cq, al, k1, qw0, qrow, r32, hi);
.LBB0_526:
	s_and_b32 s23, s18, 1
	s_xor_b32 s8, s23, 1
	s_lshl_b32 s34, s8, 9
	s_add_i32 s89, s34, 0
	s_mulk_i32 s8, 0x4800
	s_add_i32 s9, s22, 0xc0
	s_add_i32 s89, s89, 0x12000
	s_add_i32 s34, s8, 0
	s_cmp_le_i32 s9, s82
	s_cselect_b64 s[8:9], -1, 0
	s_add_i32 s42, s37, 1
	s_cmp_ge_i32 s42, s35
	s_cselect_b64 s[42:43], -1, 0
	s_and_b64 s[42:43], s[8:9], s[42:43]
	s_cmp_ge_i32 s37, s35
	s_cselect_b64 s[46:47], -1, 0
	s_and_b64 s[8:9], s[42:43], s[46:47]
	s_andn2_b64 vcc, exec, s[8:9]
	s_mov_b64 s[44:45], -1
	s_cbranch_vccz .LBB0_539
	s_add_i32 s8, s22, 0x80
	s_cmp_le_i32 s8, s82
	s_cselect_b64 s[8:9], -1, 0
	s_and_b64 s[8:9], s[8:9], s[46:47]
	s_or_b64 s[8:9], s[42:43], s[8:9]
	v_mov_b64_e32 v[96:97], v[16:17]
	v_mov_b64_e32 v[80:81], v[32:33]
	s_andn2_b64 vcc, exec, s[8:9]
	v_mov_b32_e32 v174, v226
	v_mov_b32_e32 v34, v227
	v_mov_b32_e32 v175, v228
	v_mov_b64_e32 v[94:95], v[14:15]
	v_mov_b64_e32 v[92:93], v[12:13]
	v_mov_b64_e32 v[90:91], v[10:11]
	v_mov_b64_e32 v[88:89], v[8:9]
	v_mov_b64_e32 v[86:87], v[6:7]
	v_mov_b64_e32 v[84:85], v[4:5]
	v_mov_b64_e32 v[82:83], v[2:3]
	v_mov_b64_e32 v[78:79], v[30:31]
	v_mov_b64_e32 v[76:77], v[28:29]
	v_mov_b64_e32 v[74:75], v[26:27]
	v_mov_b64_e32 v[72:73], v[24:25]
	v_mov_b64_e32 v[70:71], v[22:23]
	v_mov_b64_e32 v[68:69], v[20:21]
	v_mov_b64_e32 v[66:67], v[18:19]
	s_cbranch_vccnz .LBB0_537
	s_and_b64 s[8:9], s[42:43], exec
	s_cselect_b32 s42, 64, 0
	s_lshl_b32 s8, s42, 2
	s_add_i32 s8, s89, s8
	v_lshl_add_u32 v62, v221, 2, s8
	s_mul_i32 s8, s42, 0x90
	s_add_i32 s8, s34, s8
	v_lshlrev_b32_e32 v66, 1, v217
	ds_read_b128 v[50:53], v62 offset:128
	ds_read_b128 v[34:37], v62
	ds_read_b128 v[38:41], v62 offset:32
	ds_read_b128 v[54:57], v62 offset:160
	ds_read_b128 v[42:45], v62 offset:64
	ds_read_b128 v[58:61], v62 offset:192
	ds_read_b128 v[46:49], v62 offset:96
	ds_read_b128 v[62:65], v62 offset:224
	v_add3_u32 v78, s8, v222, v66
	ds_read_b128 v[66:69], v78 offset:4608
	ds_read_b128 v[70:73], v78
	ds_read_b128 v[74:77], v78 offset:32
	s_waitcnt lgkmcnt(6)
	s_waitcnt lgkmcnt(4)
	v_pk_add_f32 v[48:49], v[228:229], v[48:49] op_sel_hi:[0,1] neg_lo:[0,1] neg_hi:[0,1]
	v_pk_add_f32 v[46:47], v[228:229], v[46:47] op_sel_hi:[0,1] neg_lo:[0,1] neg_hi:[0,1]
	v_pk_add_f32 v[44:45], v[228:229], v[44:45] op_sel_hi:[0,1] neg_lo:[0,1] neg_hi:[0,1]
	v_pk_add_f32 v[42:43], v[228:229], v[42:43] op_sel_hi:[0,1] neg_lo:[0,1] neg_hi:[0,1]
	v_pk_add_f32 v[40:41], v[228:229], v[40:41] op_sel_hi:[0,1] neg_lo:[0,1] neg_hi:[0,1]
	v_pk_add_f32 v[38:39], v[228:229], v[38:39] op_sel_hi:[0,1] neg_lo:[0,1] neg_hi:[0,1]
	v_pk_add_f32 v[36:37], v[228:229], v[36:37] op_sel_hi:[0,1] neg_lo:[0,1] neg_hi:[0,1]
	v_pk_add_f32 v[34:35], v[228:229], v[34:35] op_sel_hi:[0,1] neg_lo:[0,1] neg_hi:[0,1]
	s_waitcnt lgkmcnt(3)
	v_pk_add_f32 v[64:65], v[228:229], v[64:65] op_sel_hi:[0,1] neg_lo:[0,1] neg_hi:[0,1]
	s_waitcnt lgkmcnt(1)
	v_mfma_f32_32x32x16_bf16 v[34:49], v[70:73], v[114:117], v[34:49]
	v_pk_add_f32 v[62:63], v[228:229], v[62:63] op_sel_hi:[0,1] neg_lo:[0,1] neg_hi:[0,1]
	v_pk_add_f32 v[60:61], v[228:229], v[60:61] op_sel_hi:[0,1] neg_lo:[0,1] neg_hi:[0,1]
	v_pk_add_f32 v[58:59], v[228:229], v[58:59] op_sel_hi:[0,1] neg_lo:[0,1] neg_hi:[0,1]
	v_pk_add_f32 v[56:57], v[228:229], v[56:57] op_sel_hi:[0,1] neg_lo:[0,1] neg_hi:[0,1]
	v_pk_add_f32 v[54:55], v[228:229], v[54:55] op_sel_hi:[0,1] neg_lo:[0,1] neg_hi:[0,1]
	v_pk_add_f32 v[52:53], v[228:229], v[52:53] op_sel_hi:[0,1] neg_lo:[0,1] neg_hi:[0,1]
	v_pk_add_f32 v[50:51], v[228:229], v[50:51] op_sel_hi:[0,1] neg_lo:[0,1] neg_hi:[0,1]
	s_waitcnt lgkmcnt(0)
	v_mfma_f32_32x32x16_bf16 v[34:49], v[74:77], v[118:121], v[34:49]
	v_mfma_f32_32x32x16_bf16 v[50:65], v[66:69], v[114:117], v[50:65]
	ds_read_b128 v[66:69], v78 offset:4640
	s_waitcnt lgkmcnt(0)
	v_mfma_f32_32x32x16_bf16 v[50:65], v[66:69], v[118:121], v[50:65]
	ds_read_b128 v[66:69], v78 offset:64
	ds_read_b128 v[70:73], v78 offset:4672
	s_waitcnt lgkmcnt(1)
	v_mfma_f32_32x32x16_bf16 v[34:49], v[66:69], v[122:125], v[34:49]
	s_waitcnt lgkmcnt(0)
	v_mfma_f32_32x32x16_bf16 v[50:65], v[70:73], v[122:125], v[50:65]
	ds_read_b128 v[66:69], v78 offset:96
	ds_read_b128 v[70:73], v78 offset:4704
	s_waitcnt lgkmcnt(1)
	v_mfma_f32_32x32x16_bf16 v[34:49], v[66:69], v[126:129], v[34:49]
	v_lshl_add_u32 v66, v223, 1, s8
	v_lshlrev_b32_e32 v67, 1, v224
	v_add3_u32 v66, v66, v67, v225
	ds_read_b64_tr_b16 v[134:135], v66 offset:36864
	ds_read_b64_tr_b16 v[136:137], v66 offset:38016
	ds_read_b64_tr_b16 v[130:131], v66 offset:36928
	ds_read_b64_tr_b16 v[132:133], v66 offset:38080
	ds_read_b64_tr_b16 v[142:143], v66 offset:39168
	ds_read_b64_tr_b16 v[144:145], v66 offset:40320
	ds_read_b64_tr_b16 v[138:139], v66 offset:39232
	ds_read_b64_tr_b16 v[140:141], v66 offset:40384
	ds_read_b64_tr_b16 v[150:151], v66 offset:41472
	ds_read_b64_tr_b16 v[152:153], v66 offset:42624
	ds_read_b64_tr_b16 v[146:147], v66 offset:41536
	ds_read_b64_tr_b16 v[148:149], v66 offset:42688
	ds_read_b64_tr_b16 v[158:159], v66 offset:43776
	ds_read_b64_tr_b16 v[160:161], v66 offset:44928
	ds_read_b64_tr_b16 v[154:155], v66 offset:43840
	ds_read_b64_tr_b16 v[156:157], v66 offset:44992
	s_waitcnt lgkmcnt(14)
	v_mfma_f32_32x32x16_bf16 v[50:65], v[70:73], v[126:129], v[50:65]
	s_add_i32 s8, s42, s22
	s_add_i32 s9, s8, 0xbf
	s_cmp_le_i32 s9, s19
	s_cbranch_scc1 .LBB0_532
; DI int crow(int r, int hi) { return (r & 3) + 8 * (r >> 2) + 4 * hi; }
; template <bool PEND> DI void fx_softmax(f32x16& p0, f32x16& p1, f32x16& q0, f32x16& q1, bf16x8 (&pw)[4], f32x16 (&o)[2], float& m, float& l, float& cqm, float cq, LAS float* al,
;                                         int k0, int qw0, int qrow, int r32, int hi) {
;     if (k0 + 63 > qw0) {
; #pragma unroll
;         for (int i = 0; i < 16; ++i) { const int kv = k0 + crow(i, hi); if (kv > qrow) p0[i] = -INFINITY; if (kv + 32 > qrow) p1[i] = -INFINITY; } }
	v_add_u32_e32 v66, s8, v221
	v_add_u32_e32 v68, 0xa0, v66
	v_add_u32_e32 v67, 0x80, v66
	v_cmp_le_i32_e64 s[42:43], v68, v168
	v_cmp_le_i32_e32 vcc, v67, v168
	s_nop 2
	v_cndmask_b32_e64 v50, v211, v50, s[42:43]
	v_cmp_lt_i32_e64 s[42:43], v67, v168
	v_add_u32_e32 v67, 0xa1, v66
	v_cmp_le_i32_e64 s[44:45], v67, v168
	v_add_u32_e32 v67, 0x82, v66
	s_nop 0
	v_cndmask_b32_e64 v51, v211, v51, s[44:45]
	v_cmp_le_i32_e64 s[44:45], v67, v168
	v_add_u32_e32 v67, 0xa2, v66
	v_cmp_le_i32_e64 s[46:47], v67, v168
	v_add_u32_e32 v67, 0x83, v66
	s_nop 0
	v_cndmask_b32_e64 v52, v211, v52, s[46:47]
	v_cmp_le_i32_e64 s[46:47], v67, v168
	v_add_u32_e32 v67, 0xa3, v66
	v_cmp_le_i32_e64 s[48:49], v67, v168
	v_add_u32_e32 v67, 0x88, v66
	s_nop 0
	v_cndmask_b32_e64 v53, v211, v53, s[48:49]
	v_cmp_le_i32_e64 s[48:49], v67, v168
	v_add_u32_e32 v67, 0xa8, v66
	v_cmp_le_i32_e64 s[50:51], v67, v168
	v_add_u32_e32 v67, 0x89, v66
	s_nop 0
	v_cndmask_b32_e64 v54, v211, v54, s[50:51]
	v_cmp_le_i32_e64 s[50:51], v67, v168
	v_add_u32_e32 v67, 0xa9, v66
	v_cmp_le_i32_e64 s[52:53], v67, v168
	v_add_u32_e32 v67, 0x8a, v66
	s_nop 0
	v_cndmask_b32_e64 v55, v211, v55, s[52:53]
	v_cmp_le_i32_e64 s[52:53], v67, v168
	v_add_u32_e32 v67, 0xaa, v66
	v_cmp_le_i32_e64 s[54:55], v67, v168
	v_add_u32_e32 v67, 0x8b, v66
	s_nop 0
	v_cndmask_b32_e64 v56, v211, v56, s[54:55]
	v_cmp_le_i32_e64 s[54:55], v67, v168
	v_add_u32_e32 v67, 0xab, v66
	v_cmp_le_i32_e64 s[56:57], v67, v168
	v_add_u32_e32 v67, 0x90, v66
	s_nop 0
	v_cndmask_b32_e64 v57, v211, v57, s[56:57]
	v_cmp_le_i32_e64 s[56:57], v67, v168
	v_add_u32_e32 v67, 0xb0, v66
	v_cmp_le_i32_e64 s[58:59], v67, v168
	v_add_u32_e32 v67, 0x91, v66
	s_nop 0
	v_cndmask_b32_e64 v58, v211, v58, s[58:59]
	v_cmp_le_i32_e64 s[58:59], v67, v168
	v_add_u32_e32 v67, 0xb1, v66
	v_cmp_le_i32_e64 s[60:61], v67, v168
	v_add_u32_e32 v67, 0x92, v66
	s_nop 0
	v_cndmask_b32_e64 v59, v211, v59, s[60:61]
	v_cmp_le_i32_e64 s[60:61], v67, v168
	v_add_u32_e32 v67, 0xb2, v66
	v_cmp_le_i32_e64 s[62:63], v67, v168
	v_add_u32_e32 v67, 0x93, v66
	s_nop 0
	v_cndmask_b32_e64 v60, v211, v60, s[62:63]
	v_cmp_le_i32_e64 s[62:63], v67, v168
	v_add_u32_e32 v67, 0xb3, v66
	v_cmp_le_i32_e64 s[64:65], v67, v168
	v_add_u32_e32 v67, 0x98, v66
	s_nop 0
	v_cndmask_b32_e64 v61, v211, v61, s[64:65]
	v_cmp_le_i32_e64 s[64:65], v67, v168
	v_add_u32_e32 v67, 0xb8, v66
	v_cmp_le_i32_e64 s[66:67], v67, v168
	v_add_u32_e32 v67, 0x99, v66
	s_nop 0
	v_cndmask_b32_e64 v62, v211, v62, s[66:67]
	v_cmp_le_i32_e64 s[66:67], v67, v168
	v_add_u32_e32 v67, 0xb9, v66
	v_cmp_le_i32_e64 s[68:69], v67, v168
	v_add_u32_e32 v67, 0x9a, v66
	s_nop 0
	v_cndmask_b32_e64 v63, v211, v63, s[68:69]
	v_cmp_le_i32_e64 s[68:69], v67, v168
	v_add_u32_e32 v67, 0xba, v66
	v_cmp_le_i32_e64 s[70:71], v67, v168
	v_add_u32_e32 v67, 0x9b, v66
	v_add_u32_e32 v66, 0xbb, v66
	v_cndmask_b32_e64 v64, v211, v64, s[70:71]
	v_cmp_le_i32_e64 s[70:71], v67, v168
	v_cmp_gt_i32_e64 s[72:73], v66, v168
	s_and_saveexec_b64 s[86:87], s[72:73]
	v_mov_b32_e32 v65, s13
	s_or_b64 exec, exec, s[86:87]
	v_cndmask_b32_e64 v35, v211, v35, s[42:43]
	v_cndmask_b32_e32 v34, v211, v34, vcc
	v_cndmask_b32_e64 v36, v211, v36, s[44:45]
	v_cndmask_b32_e64 v37, v211, v37, s[46:47]
	v_cndmask_b32_e64 v38, v211, v38, s[48:49]
	v_cndmask_b32_e64 v39, v211, v39, s[50:51]
	v_cndmask_b32_e64 v40, v211, v40, s[52:53]
	v_cndmask_b32_e64 v41, v211, v41, s[54:55]
	v_cndmask_b32_e64 v42, v211, v42, s[56:57]
	v_cndmask_b32_e64 v43, v211, v43, s[58:59]
	v_cndmask_b32_e64 v44, v211, v44, s[60:61]
	v_cndmask_b32_e64 v45, v211, v45, s[62:63]
	v_cndmask_b32_e64 v46, v211, v46, s[64:65]
	v_cndmask_b32_e64 v47, v211, v47, s[66:67]
	v_cndmask_b32_e64 v48, v211, v48, s[68:69]
	v_cndmask_b32_e64 v49, v211, v49, s[70:71]

; #define LAS __attribute__((address_space(3)))
; DI void fx_init(f32x16& p0, f32x16& p1, const LAS float* ck, float cqm, int hi) {
; #pragma unroll
;     for (int g = 0; g < 4; ++g) { const f32x4 c0 = *(const LAS f32x4*)(ck + 8 * g + 4 * hi), c1 = *(const LAS f32x4*)(ck + 32 + 8 * g + 4 * hi);
; #pragma unroll
;         for (int e = 0; e < 4; ++e) { p0[4 * g + e] = cqm - c0[e]; p1[4 * g + e] = cqm - c1[e]; } }
; }
; DI void fx_qk(f32x16& p0, f32x16& p1, const LAS bf16_t* Kt, const bf16x8 (&qr)[4], int r32, int hi) {
; #pragma unroll
;     for (int ks = 0; ks < 4; ++ks) { const bf16x8 a0 = *(const LAS bf16x8*)(Kt + r32 * 72 + 16 * ks + 8 * hi), a1 = *(const LAS bf16x8*)(Kt + (32 + r32) * 72 + 16 * ks + 8 * hi);
;         p0 = __builtin_amdgcn_mfma_f32_32x32x16_bf16(a0, qr[ks], p0, 0, 0, 0); p1 = __builtin_amdgcn_mfma_f32_32x32x16_bf16(a1, qr[ks], p1, 0, 0, 0); }
; }
; DI void fx_vfrag(bf16x8 (&vfr)[4][2], const LAS bf16_t* Vt, int lane, int hi) {
; #pragma unroll
;     for (int st = 0; st < 4; ++st)
; #pragma unroll
;         for (int db = 0; db < 2; ++db) { const LAS bf16_t* vp = Vt + (16 * st + 4 * hi + ((lane & 15) >> 2)) * 72 + 32 * db + 16 * ((lane >> 4) & 1) + 4 * (lane & 3);
;             const s16x4 lo = __builtin_bit_cast(s16x4, __builtin_amdgcn_ds_read_tr16_b64_v4i16((LAS v4i16_t*)vp));
;             const s16x4 hh = __builtin_bit_cast(s16x4, __builtin_amdgcn_ds_read_tr16_b64_v4i16((LAS v4i16_t*)(vp + 8 * 72)));
;             vfr[st][db] = __builtin_shufflevector(lo, hh, 0, 1, 2, 3, 4, 5, 6, 7); }
; }
; DI void fox_unit(int bh, int qb, const Params& p, LAS unsigned char* lds, float thr2) {
;     ...
;               fx_init(a0, a1, ckT + 64, cqm, hi); fx_init(b0, b1, ckT, cqm, hi);
;               fx_qk(a0, a1, KtT + 64 * FX_KP, qr, r32, hi);
;               fx_qk(b0, b1, KtT, qr, r32, hi);
;               fx_vfrag(vfr, VtT + 64 * FX_KP, lane, hi);
.LBB0_540:
	v_lshl_add_u32 v130, v221, 2, s89
	ds_read_b128 v[34:37], v130 offset:256
	ds_read_b128 v[38:41], v130 offset:384
	ds_read_b128 v[42:45], v130 offset:288
	ds_read_b128 v[46:49], v130 offset:416
	ds_read_b128 v[50:53], v130 offset:320
	ds_read_b128 v[54:57], v130 offset:448
	ds_read_b128 v[58:61], v130 offset:352
	ds_read_b128 v[62:65], v130 offset:480
	s_waitcnt lgkmcnt(5)
	s_waitcnt lgkmcnt(3)
	v_pk_add_f32 v[76:77], v[228:229], v[52:53] op_sel_hi:[0,1] neg_lo:[0,1] neg_hi:[0,1]
	s_waitcnt lgkmcnt(1)
	v_pk_add_f32 v[80:81], v[228:229], v[60:61] op_sel_hi:[0,1] neg_lo:[0,1] neg_hi:[0,1]
	v_pk_add_f32 v[78:79], v[228:229], v[58:59] op_sel_hi:[0,1] neg_lo:[0,1] neg_hi:[0,1]
	v_pk_add_f32 v[74:75], v[228:229], v[50:51] op_sel_hi:[0,1] neg_lo:[0,1] neg_hi:[0,1]
	v_pk_add_f32 v[72:73], v[228:229], v[44:45] op_sel_hi:[0,1] neg_lo:[0,1] neg_hi:[0,1]
	v_pk_add_f32 v[70:71], v[228:229], v[42:43] op_sel_hi:[0,1] neg_lo:[0,1] neg_hi:[0,1]
	v_pk_add_f32 v[68:69], v[228:229], v[36:37] op_sel_hi:[0,1] neg_lo:[0,1] neg_hi:[0,1]
	v_pk_add_f32 v[66:67], v[228:229], v[34:35] op_sel_hi:[0,1] neg_lo:[0,1] neg_hi:[0,1]
	s_waitcnt lgkmcnt(0)
	v_pk_add_f32 v[96:97], v[228:229], v[64:65] op_sel_hi:[0,1] neg_lo:[0,1] neg_hi:[0,1]
	v_pk_add_f32 v[94:95], v[228:229], v[62:63] op_sel_hi:[0,1] neg_lo:[0,1] neg_hi:[0,1]
	v_pk_add_f32 v[92:93], v[228:229], v[56:57] op_sel_hi:[0,1] neg_lo:[0,1] neg_hi:[0,1]
	v_pk_add_f32 v[90:91], v[228:229], v[54:55] op_sel_hi:[0,1] neg_lo:[0,1] neg_hi:[0,1]
	v_pk_add_f32 v[88:89], v[228:229], v[48:49] op_sel_hi:[0,1] neg_lo:[0,1] neg_hi:[0,1]
	v_pk_add_f32 v[86:87], v[228:229], v[46:47] op_sel_hi:[0,1] neg_lo:[0,1] neg_hi:[0,1]
	v_pk_add_f32 v[84:85], v[228:229], v[40:41] op_sel_hi:[0,1] neg_lo:[0,1] neg_hi:[0,1]
	v_pk_add_f32 v[82:83], v[228:229], v[38:39] op_sel_hi:[0,1] neg_lo:[0,1] neg_hi:[0,1]
	ds_read_b128 v[50:53], v130 offset:128
	ds_read_b128 v[34:37], v130
	ds_read_b128 v[38:41], v130 offset:32
	ds_read_b128 v[54:57], v130 offset:160
	ds_read_b128 v[42:45], v130 offset:64
	ds_read_b128 v[58:61], v130 offset:192
	ds_read_b128 v[46:49], v130 offset:96
	ds_read_b128 v[62:65], v130 offset:224
	v_lshlrev_b32_e32 v130, 1, v217
	v_add3_u32 v142, s34, v222, v130
	ds_read_b128 v[130:133], v142 offset:9216
	ds_read_b128 v[134:137], v142 offset:13824
	s_waitcnt lgkmcnt(1)
	v_mfma_f32_32x32x16_bf16 v[66:81], v[130:133], v[114:117], v[66:81]
	v_pk_add_f32 v[48:49], v[228:229], v[48:49] op_sel_hi:[0,1] neg_lo:[0,1] neg_hi:[0,1]
	v_pk_add_f32 v[46:47], v[228:229], v[46:47] op_sel_hi:[0,1] neg_lo:[0,1] neg_hi:[0,1]
	v_pk_add_f32 v[44:45], v[228:229], v[44:45] op_sel_hi:[0,1] neg_lo:[0,1] neg_hi:[0,1]
	s_waitcnt lgkmcnt(0)
	v_mfma_f32_32x32x16_bf16 v[82:97], v[134:137], v[114:117], v[82:97]
	ds_read_b128 v[130:133], v142 offset:9248
	ds_read_b128 v[134:137], v142 offset:13856
	v_pk_add_f32 v[42:43], v[228:229], v[42:43] op_sel_hi:[0,1] neg_lo:[0,1] neg_hi:[0,1]
	v_pk_add_f32 v[40:41], v[228:229], v[40:41] op_sel_hi:[0,1] neg_lo:[0,1] neg_hi:[0,1]
	v_pk_add_f32 v[38:39], v[228:229], v[38:39] op_sel_hi:[0,1] neg_lo:[0,1] neg_hi:[0,1]
	s_waitcnt lgkmcnt(1)
	v_mfma_f32_32x32x16_bf16 v[66:81], v[130:133], v[118:121], v[66:81]
	v_pk_add_f32 v[36:37], v[228:229], v[36:37] op_sel_hi:[0,1] neg_lo:[0,1] neg_hi:[0,1]
	v_pk_add_f32 v[34:35], v[228:229], v[34:35] op_sel_hi:[0,1] neg_lo:[0,1] neg_hi:[0,1]
	v_pk_add_f32 v[64:65], v[228:229], v[64:65] op_sel_hi:[0,1] neg_lo:[0,1] neg_hi:[0,1]
	v_pk_add_f32 v[62:63], v[228:229], v[62:63] op_sel_hi:[0,1] neg_lo:[0,1] neg_hi:[0,1]
	s_waitcnt lgkmcnt(0)
	v_mfma_f32_32x32x16_bf16 v[82:97], v[134:137], v[118:121], v[82:97]
	ds_read_b128 v[130:133], v142 offset:9280
	ds_read_b128 v[134:137], v142 offset:13888
	v_pk_add_f32 v[60:61], v[228:229], v[60:61] op_sel_hi:[0,1] neg_lo:[0,1] neg_hi:[0,1]
	v_pk_add_f32 v[58:59], v[228:229], v[58:59] op_sel_hi:[0,1] neg_lo:[0,1] neg_hi:[0,1]
	v_pk_add_f32 v[56:57], v[228:229], v[56:57] op_sel_hi:[0,1] neg_lo:[0,1] neg_hi:[0,1]
	s_waitcnt lgkmcnt(1)
	v_mfma_f32_32x32x16_bf16 v[66:81], v[130:133], v[122:125], v[66:81]
	v_pk_add_f32 v[54:55], v[228:229], v[54:55] op_sel_hi:[0,1] neg_lo:[0,1] neg_hi:[0,1]
	v_pk_add_f32 v[52:53], v[228:229], v[52:53] op_sel_hi:[0,1] neg_lo:[0,1] neg_hi:[0,1]
	v_pk_add_f32 v[50:51], v[228:229], v[50:51] op_sel_hi:[0,1] neg_lo:[0,1] neg_hi:[0,1]
	s_waitcnt lgkmcnt(0)
	v_mfma_f32_32x32x16_bf16 v[82:97], v[134:137], v[122:125], v[82:97]
	ds_read_b128 v[130:133], v142 offset:9312
	ds_read_b128 v[134:137], v142 offset:13920
	s_waitcnt lgkmcnt(1)
	v_mfma_f32_32x32x16_bf16 v[66:81], v[130:133], v[126:129], v[66:81]
	s_waitcnt lgkmcnt(0)
	v_mfma_f32_32x32x16_bf16 v[82:97], v[134:137], v[126:129], v[82:97]
	ds_read_b128 v[130:133], v142 offset:4608
	ds_read_b128 v[134:137], v142
	ds_read_b128 v[138:141], v142 offset:32
	s_waitcnt lgkmcnt(1)
	v_mfma_f32_32x32x16_bf16 v[34:49], v[134:137], v[114:117], v[34:49]
	v_mfma_f32_32x32x16_bf16 v[50:65], v[130:133], v[114:117], v[50:65]
	ds_read_b128 v[130:133], v142 offset:4640
	s_waitcnt lgkmcnt(1)
	v_mfma_f32_32x32x16_bf16 v[34:49], v[138:141], v[118:121], v[34:49]
	s_waitcnt lgkmcnt(0)
	v_mfma_f32_32x32x16_bf16 v[50:65], v[130:133], v[118:121], v[50:65]
	ds_read_b128 v[130:133], v142 offset:64
	ds_read_b128 v[134:137], v142 offset:4672
	s_waitcnt lgkmcnt(1)
	v_mfma_f32_32x32x16_bf16 v[34:49], v[130:133], v[122:125], v[34:49]
	s_waitcnt lgkmcnt(0)
	v_mfma_f32_32x32x16_bf16 v[50:65], v[134:137], v[122:125], v[50:65]
	ds_read_b128 v[130:133], v142 offset:96
	ds_read_b128 v[134:137], v142 offset:4704
	s_waitcnt lgkmcnt(1)
	v_mfma_f32_32x32x16_bf16 v[34:49], v[130:133], v[126:129], v[34:49]
	v_lshlrev_b32_e32 v130, 1, v223
	v_lshlrev_b32_e32 v131, 1, v224
	v_add3_u32 v130, s34, v130, v131
	v_add_u32_e32 v230, v130, v225
	s_waitcnt lgkmcnt(0)
	v_mfma_f32_32x32x16_bf16 v[50:65], v[134:137], v[126:129], v[50:65]
	ds_read_b64_tr_b16 v[134:135], v230 offset:46080
	ds_read_b64_tr_b16 v[136:137], v230 offset:47232
	ds_read_b64_tr_b16 v[138:139], v230 offset:46144
	ds_read_b64_tr_b16 v[140:141], v230 offset:47296
	ds_read_b64_tr_b16 v[150:151], v230 offset:48384
	ds_read_b64_tr_b16 v[152:153], v230 offset:49536
	ds_read_b64_tr_b16 v[146:147], v230 offset:48448
	ds_read_b64_tr_b16 v[148:149], v230 offset:49600
	ds_read_b64_tr_b16 v[154:155], v230 offset:50688
	ds_read_b64_tr_b16 v[156:157], v230 offset:51840
	ds_read_b64_tr_b16 v[158:159], v230 offset:50752
	ds_read_b64_tr_b16 v[160:161], v230 offset:51904
	ds_read_b64_tr_b16 v[142:143], v230 offset:52992
	ds_read_b64_tr_b16 v[144:145], v230 offset:54144
	ds_read_b64_tr_b16 v[130:131], v230 offset:53056
	ds_read_b64_tr_b16 v[132:133], v230 offset:54208
	s_add_i32 s8, s22, 0xff
	s_cmp_le_i32 s8, s19
	v_add_u32_e32 v229, s22, v221
	s_cbranch_scc1 .LBB0_544
; DI int crow(int r, int hi) { return (r & 3) + 8 * (r >> 2) + 4 * hi; }
; template <bool PEND> DI void fx_softmax(f32x16& p0, f32x16& p1, f32x16& q0, f32x16& q1, bf16x8 (&pw)[4], f32x16 (&o)[2], float& m, float& l, float& cqm, float cq, LAS float* al,
;                                         int k0, int qw0, int qrow, int r32, int hi) {
;     if (k0 + 63 > qw0) {
; #pragma unroll
;         for (int i = 0; i < 16; ++i) { const int kv = k0 + crow(i, hi); if (kv > qrow) p0[i] = -INFINITY; if (kv + 32 > qrow) p1[i] = -INFINITY; } }
	v_add_u32_e32 v175, 0xe0, v229
	v_add_u32_e32 v174, 0xc0, v229
	v_cmp_le_i32_e64 s[42:43], v175, v168
	v_cmp_le_i32_e32 vcc, v174, v168
	s_nop 0
	v_cndmask_b32_e64 v82, v211, v82, s[42:43]
	v_cmp_lt_i32_e64 s[42:43], v174, v168
	v_add_u32_e32 v174, 0xe1, v229
	v_cmp_le_i32_e64 s[44:45], v174, v168
	v_add_u32_e32 v174, 0xc2, v229
	s_nop 0
	v_cndmask_b32_e64 v83, v211, v83, s[44:45]
	v_cmp_le_i32_e64 s[44:45], v174, v168
	v_add_u32_e32 v174, 0xe2, v229
	v_cmp_le_i32_e64 s[46:47], v174, v168
	v_add_u32_e32 v174, 0xc3, v229
	s_nop 0
	v_cndmask_b32_e64 v84, v211, v84, s[46:47]
	v_cmp_le_i32_e64 s[46:47], v174, v168
	v_add_u32_e32 v174, 0xe3, v229
	v_cmp_le_i32_e64 s[48:49], v174, v168
	v_add_u32_e32 v174, 0xc8, v229
	s_nop 0
	v_cndmask_b32_e64 v85, v211, v85, s[48:49]
	v_cmp_le_i32_e64 s[48:49], v174, v168
	v_add_u32_e32 v174, 0xe8, v229
	v_cmp_le_i32_e64 s[50:51], v174, v168
	v_add_u32_e32 v174, 0xc9, v229
	s_nop 0
	v_cndmask_b32_e64 v86, v211, v86, s[50:51]
	v_cmp_le_i32_e64 s[50:51], v174, v168
	v_add_u32_e32 v174, 0xe9, v229
	v_cmp_le_i32_e64 s[52:53], v174, v168
	v_add_u32_e32 v174, 0xca, v229
	s_nop 0
	v_cndmask_b32_e64 v87, v211, v87, s[52:53]
	v_cmp_le_i32_e64 s[52:53], v174, v168
	v_add_u32_e32 v174, 0xea, v229
	v_cmp_le_i32_e64 s[54:55], v174, v168
	v_add_u32_e32 v174, 0xcb, v229
	s_nop 0
	v_cndmask_b32_e64 v88, v211, v88, s[54:55]
	v_cmp_le_i32_e64 s[54:55], v174, v168
	v_add_u32_e32 v174, 0xeb, v229
	v_cmp_le_i32_e64 s[56:57], v174, v168
	v_add_u32_e32 v174, 0xd0, v229
	s_nop 0
	v_cndmask_b32_e64 v89, v211, v89, s[56:57]
	v_cmp_le_i32_e64 s[56:57], v174, v168
	v_add_u32_e32 v174, 0xf0, v229
	v_cmp_le_i32_e64 s[58:59], v174, v168
	v_add_u32_e32 v174, 0xd1, v229
	s_nop 0
	v_cndmask_b32_e64 v90, v211, v90, s[58:59]
	v_cmp_le_i32_e64 s[58:59], v174, v168
	v_add_u32_e32 v174, 0xf1, v229
	v_cmp_le_i32_e64 s[60:61], v174, v168
	v_add_u32_e32 v174, 0xd2, v229
	s_nop 0
	v_cndmask_b32_e64 v91, v211, v91, s[60:61]
	v_cmp_le_i32_e64 s[60:61], v174, v168
	v_add_u32_e32 v174, 0xf2, v229
	v_cmp_le_i32_e64 s[62:63], v174, v168
	v_add_u32_e32 v174, 0xd3, v229
	s_nop 0
	v_cndmask_b32_e64 v92, v211, v92, s[62:63]
	v_cmp_le_i32_e64 s[62:63], v174, v168
	v_add_u32_e32 v174, 0xf3, v229
	v_cmp_le_i32_e64 s[64:65], v174, v168
	v_add_u32_e32 v174, 0xd8, v229
	s_nop 0
	v_cndmask_b32_e64 v93, v211, v93, s[64:65]
	v_cmp_le_i32_e64 s[64:65], v174, v168
	v_add_u32_e32 v174, 0xf8, v229
	v_cmp_le_i32_e64 s[66:67], v174, v168
	v_add_u32_e32 v174, 0xd9, v229
	s_nop 0
	v_cndmask_b32_e64 v94, v211, v94, s[66:67]
	v_cmp_le_i32_e64 s[66:67], v174, v168
	v_add_u32_e32 v174, 0xf9, v229
	v_cmp_le_i32_e64 s[68:69], v174, v168
	v_add_u32_e32 v174, 0xda, v229
	s_nop 0
	v_cndmask_b32_e64 v95, v211, v95, s[68:69]
	v_cmp_le_i32_e64 s[68:69], v174, v168
	v_add_u32_e32 v174, 0xfa, v229
	v_cmp_le_i32_e64 s[70:71], v174, v168
	v_add_u32_e32 v174, 0xdb, v229
	s_nop 0
	v_cndmask_b32_e64 v96, v211, v96, s[70:71]
	v_cmp_le_i32_e64 s[70:71], v174, v168
	v_add_u32_e32 v174, 0xfb, v229
	v_cmp_gt_i32_e64 s[72:73], v174, v168
	s_and_saveexec_b64 s[86:87], s[72:73]
	v_mov_b32_e32 v97, s13
	s_or_b64 exec, exec, s[86:87]
	v_cndmask_b32_e64 v67, v211, v67, s[42:43]
	v_cndmask_b32_e32 v66, v211, v66, vcc
	v_cndmask_b32_e64 v68, v211, v68, s[44:45]
	v_cndmask_b32_e64 v69, v211, v69, s[46:47]
	v_cndmask_b32_e64 v70, v211, v70, s[48:49]
	v_cndmask_b32_e64 v71, v211, v71, s[50:51]
	v_cndmask_b32_e64 v72, v211, v72, s[52:53]
	v_cndmask_b32_e64 v73, v211, v73, s[54:55]
	v_cndmask_b32_e64 v74, v211, v74, s[56:57]
	v_cndmask_b32_e64 v75, v211, v75, s[58:59]
	v_cndmask_b32_e64 v76, v211, v76, s[60:61]
	v_cndmask_b32_e64 v77, v211, v77, s[62:63]
	v_cndmask_b32_e64 v78, v211, v78, s[64:65]
	v_cndmask_b32_e64 v79, v211, v79, s[66:67]
	v_cndmask_b32_e64 v80, v211, v80, s[68:69]
	v_cndmask_b32_e64 v81, v211, v81, s[70:71]
